# norm phase: 64-lane sums via DPP row adds + readlane instead of 6-step ds_bpermute butterflies
# speedup vs baseline: 1.0034x; 1.0034x over previous
.LBB0_149:
	s_or_b64 exec, exec, s[0:1]
	v_min_i32_e32 v56, 0x10000, v54
	v_ashrrev_i32_e32 v56, 13, v56
	v_mul_i32_i24_e32 v56, 0x1800, v56
	v_ashrrev_i32_e32 v57, 31, v56
	v_lshl_add_u64 v[56:57], v[56:57], 2, s[24:25]
	v_lshl_add_u64 v[78:79], v[56:57], 0, v[48:49]
	v_add_co_u32_e64 v56, s[0:1], s10, v78
	s_waitcnt vmcnt(3)
	v_pk_mul_f32 v[80:81], v[44:45], v[44:45]
	v_addc_co_u32_e64 v57, s[0:1], 0, v79, s[0:1]
	global_load_dwordx4 v[70:73], v[56:57], off
	global_load_dwordx4 v[74:77], v[78:79], off
	v_pk_mul_f32 v[56:57], v[46:47], v[46:47]
	s_waitcnt vmcnt(4)
	v_pk_mul_f32 v[82:83], v[42:43], v[42:43]
	v_pk_mul_f32 v[84:85], v[40:41], v[40:41]
	v_pk_mov_b32 v[90:91], v[80:81], v[56:57] op_sel:[1,0]
	v_mov_b32_e32 v81, v57
	v_pk_mov_b32 v[56:57], v[84:85], v[82:83] op_sel:[1,0]
	v_mov_b32_e32 v85, v83
	s_waitcnt vmcnt(2)
	v_mul_f32_e32 v89, v33, v33
	v_mul_f32_e32 v86, v37, v37
	v_mul_f32_e32 v88, v39, v39
	v_pk_add_f32 v[80:81], v[90:91], v[80:81]
	v_pk_add_f32 v[56:57], v[56:57], v[84:85]
	v_mul_f32_e32 v69, v32, v32
	v_mul_f32_e32 v92, v34, v34
	v_mul_f32_e32 v93, v35, v35
	v_pk_fma_f32 v[82:83], v[36:37], v[36:37], v[86:87] op_sel_hi:[1,1,0]
	v_pk_fma_f32 v[86:87], v[38:39], v[38:39], v[88:89] op_sel_hi:[1,1,0]
	v_pk_add_f32 v[80:81], v[80:81], v[80:81] op_sel:[0,1] op_sel_hi:[1,0]
	v_pk_add_f32 v[56:57], v[56:57], v[56:57] op_sel:[0,1] op_sel_hi:[1,0]
	v_mov_b32_e32 v83, v92
	v_mov_b32_e32 v87, v93
	v_mov_b32_e32 v81, v69
	v_mov_b32_e32 v57, v89
	v_pk_add_f32 v[82:83], v[82:83], v[86:87]
	v_pk_add_f32 v[56:57], v[80:81], v[56:57]
	v_lshlrev_b64 v[54:55], 11, v[54:55]
	v_pk_add_f32 v[56:57], v[56:57], v[82:83]
	v_lshl_add_u64 v[82:83], v[50:51], 0, v[54:55]
	v_add_f32_e32 v56, v56, v57
	s_nop 1
	v_add_f32_dpp v56, v56, v56 quad_perm:[1,0,3,2] row_mask:0xf bank_mask:0xf bound_ctrl:1
	s_nop 1
	v_add_f32_dpp v56, v56, v56 quad_perm:[2,3,0,1] row_mask:0xf bank_mask:0xf bound_ctrl:1
	s_nop 1
	v_add_f32_dpp v56, v56, v56 row_half_mirror row_mask:0xf bank_mask:0xf bound_ctrl:1
	s_nop 1
	v_add_f32_dpp v56, v56, v56 row_mirror row_mask:0xf bank_mask:0xf bound_ctrl:1
	s_nop 1
	v_readlane_b32 s98, v56, 0
	v_readlane_b32 s99, v56, 16
	v_readlane_b32 s100, v56, 32
	v_readlane_b32 s101, v56, 48
	s_nop 1
	v_mov_b32_e32 v57, s98
	v_add_f32_e32 v57, s99, v57
	v_mov_b32_e32 v56, s100
	v_add_f32_e32 v56, s101, v56
	v_add_f32_e32 v56, v56, v57
	v_lshl_add_u64 v[84:85], v[78:79], 0, s[6:7]
	v_fmamk_f32 v56, v56, 0x3a800000, v68
	v_rsq_f32_e32 v80, v56
	s_waitcnt vmcnt(1)
	v_pk_add_f32 v[54:55], v[72:73], 1.0 op_sel_hi:[1,0]
	v_pk_mul_f32 v[46:47], v[46:47], v[80:81] op_sel_hi:[1,0]
	v_pk_mul_f32 v[44:45], v[44:45], v[80:81] op_sel_hi:[1,0]
	v_pk_mul_f32 v[46:47], v[2:3], v[46:47]
	v_pk_mul_f32 v[44:45], v[0:1], v[44:45]
	v_pk_add_f32 v[56:57], v[70:71], 1.0 op_sel_hi:[1,0]
	s_waitcnt vmcnt(0)
	v_pk_fma_f32 v[46:47], v[54:55], v[46:47], v[76:77]
	v_pk_fma_f32 v[44:45], v[56:57], v[44:45], v[74:75]
	v_pk_mul_f32 v[42:43], v[42:43], v[80:81] op_sel_hi:[1,0]
	v_cvt_pk_bf16_f32 v44, v44, v45
	v_cvt_pk_bf16_f32 v45, v46, v47
	global_store_dwordx2 v[82:83], v[44:45], off
	global_load_dwordx4 v[44:47], v[84:85], off offset:1024
	s_nop 0
	global_load_dwordx4 v[54:57], v[78:79], off offset:1024
	v_pk_mul_f32 v[40:41], v[40:41], v[80:81] op_sel_hi:[1,0]
	v_pk_mul_f32 v[42:43], v[6:7], v[42:43]
	v_pk_mul_f32 v[40:41], v[4:5], v[40:41]
	v_pk_mul_f32 v[38:39], v[38:39], v[80:81] op_sel_hi:[1,0]
	v_pk_mul_f32 v[36:37], v[36:37], v[80:81] op_sel_hi:[1,0]
	v_pk_mul_f32 v[38:39], v[10:11], v[38:39]
	v_pk_mul_f32 v[36:37], v[8:9], v[36:37]
	v_pk_mul_f32 v[34:35], v[34:35], v[80:81] op_sel_hi:[1,0]
	v_pk_mul_f32 v[32:33], v[32:33], v[80:81] op_sel_hi:[1,0]
	v_pk_mul_f32 v[34:35], v[14:15], v[34:35]
	v_pk_mul_f32 v[32:33], v[12:13], v[32:33]
	s_waitcnt vmcnt(1)
	v_pk_add_f32 v[46:47], v[46:47], 1.0 op_sel_hi:[1,0]
	v_pk_add_f32 v[44:45], v[44:45], 1.0 op_sel_hi:[1,0]
	s_waitcnt vmcnt(0)
	v_pk_fma_f32 v[42:43], v[46:47], v[42:43], v[56:57]
	v_pk_fma_f32 v[40:41], v[44:45], v[40:41], v[54:55]
	v_mul_f32_e32 v54, v17, v17
	v_cvt_pk_bf16_f32 v40, v40, v41
	v_cvt_pk_bf16_f32 v41, v42, v43
	global_store_dwordx2 v[82:83], v[40:41], off offset:512
	global_load_dwordx4 v[40:43], v[84:85], off offset:2048
	s_nop 0
	global_load_dwordx4 v[44:47], v[78:79], off offset:2048
	v_mul_f32_e32 v55, v19, v19
	v_mul_f32_e32 v56, v29, v29
	v_mul_f32_e32 v57, v31, v31
	v_fmac_f32_e32 v54, v16, v16
	v_fmac_f32_e32 v55, v18, v18
	v_fmac_f32_e32 v56, v28, v28
	v_fmac_f32_e32 v57, v30, v30
	s_waitcnt vmcnt(1)
	v_pk_add_f32 v[42:43], v[42:43], 1.0 op_sel_hi:[1,0]
	v_pk_add_f32 v[40:41], v[40:41], 1.0 op_sel_hi:[1,0]
	s_waitcnt vmcnt(0)
	v_pk_fma_f32 v[38:39], v[42:43], v[38:39], v[46:47]
	v_pk_fma_f32 v[36:37], v[40:41], v[36:37], v[44:45]
	v_mul_f32_e32 v46, v25, v25
	v_cvt_pk_bf16_f32 v36, v36, v37
	v_cvt_pk_bf16_f32 v37, v38, v39
	global_store_dwordx2 v[82:83], v[36:37], off offset:1024
	global_load_dwordx4 v[38:41], v[84:85], off offset:3072
	global_load_dwordx4 v[42:45], v[78:79], off offset:3072
	v_mul_f32_e32 v36, v21, v21
	v_mul_f32_e32 v37, v23, v23
	v_mul_f32_e32 v47, v27, v27
	v_fmac_f32_e32 v36, v20, v20
	v_fmac_f32_e32 v37, v22, v22
	v_fmac_f32_e32 v46, v24, v24
	v_fmac_f32_e32 v47, v26, v26
	v_add_f32_e32 v36, v36, v37
	v_add_f32_e32 v37, v46, v47
	v_add_f32_e32 v46, v54, v55
	v_add_f32_e32 v36, v36, v37
	v_add_f32_e32 v47, v56, v57
	v_add_f32_e32 v36, v36, v46
	v_add_f32_e32 v36, v36, v47
	s_nop 1
	v_add_f32_dpp v36, v36, v36 quad_perm:[1,0,3,2] row_mask:0xf bank_mask:0xf bound_ctrl:1
	s_nop 1
	v_add_f32_dpp v36, v36, v36 quad_perm:[2,3,0,1] row_mask:0xf bank_mask:0xf bound_ctrl:1
	s_nop 1
	v_add_f32_dpp v36, v36, v36 row_half_mirror row_mask:0xf bank_mask:0xf bound_ctrl:1
	s_nop 1
	v_add_f32_dpp v36, v36, v36 row_mirror row_mask:0xf bank_mask:0xf bound_ctrl:1
	s_nop 1
	v_readlane_b32 s98, v36, 0
	v_readlane_b32 s99, v36, 16
	v_readlane_b32 s100, v36, 32
	v_readlane_b32 s101, v36, 48
	s_nop 1
	v_mov_b32_e32 v37, s98
	v_add_f32_e32 v37, s99, v37
	v_mov_b32_e32 v36, s100
	v_add_f32_e32 v36, s101, v36
	v_add_f32_e32 v36, v36, v37
	s_waitcnt vmcnt(1)
	v_pk_add_f32 v[40:41], v[40:41], 1.0 op_sel_hi:[1,0]
	v_pk_add_f32 v[38:39], v[38:39], 1.0 op_sel_hi:[1,0]
	s_waitcnt vmcnt(0)
	v_pk_fma_f32 v[34:35], v[34:35], v[40:41], v[44:45]
	v_pk_fma_f32 v[32:33], v[32:33], v[38:39], v[42:43]
	s_nop 0
	v_cvt_pk_bf16_f32 v32, v32, v33
	v_cvt_pk_bf16_f32 v33, v34, v35
	global_store_dwordx2 v[82:83], v[32:33], off offset:1536
	s_and_saveexec_b64 s[0:1], vcc
	s_cbranch_execz .LBB0_140
	v_min_i32_e32 v32, 0x10000, v52
	v_ashrrev_i32_e32 v32, 13, v32
	v_mul_i32_i24_e32 v32, 0x1800, v32
	v_ashrrev_i32_e32 v33, 31, v32
	v_lshl_add_u64 v[32:33], v[32:33], 2, s[24:25]
	v_lshl_add_u64 v[42:43], v[32:33], 0, v[48:49]
	v_add_co_u32_e32 v32, vcc, s10, v42
	s_waitcnt lgkmcnt(0)
	v_addc_co_u32_e32 v33, vcc, 0, v43, vcc
	global_load_dwordx4 v[32:35], v[32:33], off
	s_nop 0
	global_load_dwordx4 v[38:41], v[42:43], off
	v_fmamk_f32 v36, v36, 0x3a800000, v68
	v_rsq_f32_e32 v36, v36
	v_lshlrev_b64 v[44:45], 11, v[52:53]
	v_lshl_add_u64 v[44:45], v[50:51], 0, v[44:45]
	v_lshl_add_u64 v[46:47], v[42:43], 0, s[6:7]
	v_pk_mul_f32 v[22:23], v[22:23], v[36:37] op_sel_hi:[1,0]
	v_pk_mul_f32 v[20:21], v[20:21], v[36:37] op_sel_hi:[1,0]
	v_pk_mul_f32 v[22:23], v[2:3], v[22:23]
	v_pk_mul_f32 v[20:21], v[0:1], v[20:21]
	v_pk_mul_f32 v[26:27], v[26:27], v[36:37] op_sel_hi:[1,0]
	v_pk_mul_f32 v[24:25], v[24:25], v[36:37] op_sel_hi:[1,0]
	v_pk_mul_f32 v[26:27], v[6:7], v[26:27]
	v_pk_mul_f32 v[24:25], v[4:5], v[24:25]
	v_pk_mul_f32 v[18:19], v[18:19], v[36:37] op_sel_hi:[1,0]
	v_pk_mul_f32 v[16:17], v[16:17], v[36:37] op_sel_hi:[1,0]
	v_pk_mul_f32 v[18:19], v[10:11], v[18:19]
	v_pk_mul_f32 v[16:17], v[8:9], v[16:17]
	s_waitcnt vmcnt(1)
	v_pk_add_f32 v[34:35], v[34:35], 1.0 op_sel_hi:[1,0]
	v_pk_add_f32 v[32:33], v[32:33], 1.0 op_sel_hi:[1,0]
	s_waitcnt vmcnt(0)
	v_pk_fma_f32 v[22:23], v[22:23], v[34:35], v[40:41]
	v_pk_fma_f32 v[20:21], v[20:21], v[32:33], v[38:39]
	s_nop 0
	v_cvt_pk_bf16_f32 v20, v20, v21
	v_cvt_pk_bf16_f32 v21, v22, v23
	global_store_dwordx2 v[44:45], v[20:21], off
	global_load_dwordx4 v[20:23], v[46:47], off offset:1024
	s_nop 0
	global_load_dwordx4 v[32:35], v[42:43], off offset:1024
	s_waitcnt vmcnt(1)
	v_pk_add_f32 v[22:23], v[22:23], 1.0 op_sel_hi:[1,0]
	v_pk_add_f32 v[20:21], v[20:21], 1.0 op_sel_hi:[1,0]
	s_waitcnt vmcnt(0)
	v_pk_fma_f32 v[22:23], v[26:27], v[22:23], v[34:35]
	v_pk_fma_f32 v[20:21], v[24:25], v[20:21], v[32:33]
	s_nop 0
	v_cvt_pk_bf16_f32 v20, v20, v21
	v_cvt_pk_bf16_f32 v21, v22, v23
	global_store_dwordx2 v[44:45], v[20:21], off offset:512
	global_load_dwordx4 v[20:23], v[46:47], off offset:2048
	s_nop 0
	global_load_dwordx4 v[24:27], v[42:43], off offset:2048
	s_waitcnt vmcnt(1)
	v_pk_add_f32 v[22:23], v[22:23], 1.0 op_sel_hi:[1,0]
	v_pk_add_f32 v[20:21], v[20:21], 1.0 op_sel_hi:[1,0]
	s_waitcnt vmcnt(0)
	v_pk_fma_f32 v[18:19], v[18:19], v[22:23], v[26:27]
	v_pk_fma_f32 v[16:17], v[16:17], v[20:21], v[24:25]
	v_pk_mul_f32 v[24:25], v[30:31], v[36:37] op_sel_hi:[1,0]
	v_cvt_pk_bf16_f32 v16, v16, v17
	v_cvt_pk_bf16_f32 v17, v18, v19
	global_store_dwordx2 v[44:45], v[16:17], off offset:1024
	global_load_dwordx4 v[16:19], v[46:47], off offset:3072
	s_nop 0
	global_load_dwordx4 v[20:23], v[42:43], off offset:3072
	v_pk_mul_f32 v[26:27], v[28:29], v[36:37] op_sel_hi:[1,0]
	v_pk_mul_f32 v[24:25], v[14:15], v[24:25]
	v_pk_mul_f32 v[26:27], v[12:13], v[26:27]
	s_waitcnt vmcnt(1)
	v_pk_add_f32 v[18:19], v[18:19], 1.0 op_sel_hi:[1,0]
	v_pk_add_f32 v[16:17], v[16:17], 1.0 op_sel_hi:[1,0]
	s_waitcnt vmcnt(0)
	v_pk_fma_f32 v[18:19], v[24:25], v[18:19], v[22:23]
	v_pk_fma_f32 v[16:17], v[26:27], v[16:17], v[20:21]
	s_nop 0
	v_cvt_pk_bf16_f32 v16, v16, v17
	v_cvt_pk_bf16_f32 v17, v18, v19
	global_store_dwordx2 v[44:45], v[16:17], off offset:1536
	s_branch .LBB0_140
